# P0: conv_matrix tile->vblock map rotated by 352 so vblocks with the meta rows convert one W_in tile instead of two
# speedup vs baseline: 1.0066x; 1.0006x over previous
; __device__ __forceinline__ void conv_matrix(const float* src, bf16_t* dst, int K, int N, int Npad, int maptype, char* smem, int start, int stride) {
;   const int nkt = K / 64, nnt = Npad / 64;
;   for (int id = start; id < nkt * nnt; id += stride) conv_tile(src, dst, K, N, (id % nkt) * 64, (id / nkt) * 64, maptype, smem);
; }
; __device__ __forceinline__ void run_phase(CP p, int ph, char* smem_full) {
;     ...
;       conv_matrix(p.in[6] + (size_t)l * D * MIXIN, WA, D, MIXIN, NIN_PAD, 0, smem, vb, NVB);
.LBB0_932:
	s_cmpk_eq_i32 s46, 0x100
	s_cbranch_scc0 .Lp0_nomap
	s_addk_i32 s54, 0x160
	s_and_b32 s54, s54, 0x1ff
